# prep waves: LoRA-operand waits counted past the ring stores; READY publish of the previous chunk deferred to the end of the next chunk's store block with a counted wait (store drain overlapped with co
# speedup vs baseline: 1.0155x; 1.0007x over previous
; #define LAS __attribute__((address_space(3)))
; #define RD_PREFETCH_A(cc) do { const int soA_ = (b * SEQ + 16 * (cc)) * 256; \
;                 _Pragma("unroll") for (int ks = 0; ks < 3; ++ks) { nAW[ks] = __builtin_bit_cast(bf16x8, __builtin_amdgcn_raw_buffer_load_b128(rsWS, voA + 64 * ks, (int)WS_AW + soA_, 0)); nAA[ks] = __builtin_bit_cast(bf16x8, __builtin_amdgcn_raw_buffer_load_b128(rsWS, voA + 64 * ks, (int)WS_AA + soA_, 0)); } } while (0)
; __device__ void phase_rwkv_dist(const Params& p, LAS unsigned char* lds, int wg, int nwg) {
;     ...
;             LAS const unsigned char* wb = lds + RC_W2H + (r * 104 + 8 * q) * 2;
;             LAS const float* cq = cst + 4 * q;
;             asm volatile("" : "+v"(wb), "+v"(cq));
;             { const int c0 = 6 * qw + pw; if (c0 < RC_NCHK) { RD_PREFETCH_A(c0); } }
;             for (int cj = 0; cj < 2 * ((RC_NCHK + 23) / 24); ++cj) {
;                 const int ci = 24 * (cj >> 1) + 6 * qw + pw + 3 * (cj & 1); if (ci >= RC_NCHK) continue;
;                 const int cn = 24 * ((cj + 1) >> 1) + 6 * qw + pw + 3 * ((cj + 1) & 1);
;                 RD_PREFETCH_R(ci);
.LBB0_650:
	s_ashr_i32 s1, s0, 31
	s_lshl_b64 s[0:1], s[0:1], 13
	v_or_b32_e32 v2, s0, v148
	s_lshl_b32 s0, s94, 9
	v_mov_b32_e32 v3, s1
	s_ashr_i32 s1, s0, 31
	s_lshl_b32 s18, s94, 20
	s_lshl_b64 s[0:1], s[0:1], 2
	v_readlane_b32 s2, v254, 0
	s_add_u32 s19, s2, s0
	v_readlane_b32 s2, v254, 2
	s_addc_u32 s40, s2, s1
	s_lshl_b32 s2, s6, 3
	v_readlane_b32 s6, v253, 47
	v_readlane_b32 s7, v253, 48
	s_add_u32 s58, s6, s2
	s_addc_u32 s59, s7, 0
	v_readlane_b32 s2, v253, 62
	s_add_u32 s41, s2, s0
	s_addc_u32 s42, s45, s1
	s_mov_b32 s43, 0
	s_mov_b64 s[0:1], 0
	s_waitcnt vmcnt(0)
	s_branch .LBB0_653

; __device__ void phase_rwkv_dist(const Params& p, LAS unsigned char* lds, int wg, int nwg) {
;     ...
;                 asm volatile("s_waitcnt vmcnt(0)" ::: "memory");
;                 __hip_atomic_store(READY + bh * 512 + ci, 1u, __ATOMIC_RELAXED, __HIP_MEMORY_SCOPE_AGENT);
.Lrst13d:
	s_cmp_lt_i32 s90, 0
	s_cbranch_scc1 .Lprep_nopend
	s_cmpk_lt_i32 s62, 0x1e0
	s_cbranch_scc1 .Lprep_pubw
	s_waitcnt vmcnt(15)
.Lprep_pubw:
	s_waitcnt vmcnt(37)
	s_lshl_b32 s86, s90, 2
	s_add_u32 s86, s41, s86
	s_addc_u32 s87, s42, 0
	s_cmp_eq_u32 s91, 0
	s_cbranch_scc1 .Lrfl0s
	global_store_dword v1, v218, s[86:87]
	s_branch .Lrfl0d

; __device__ void phase_rwkv_dist(const Params& p, LAS unsigned char* lds, int wg, int nwg) {
;     ...
;                 asm volatile("s_waitcnt vmcnt(0)" ::: "memory");
;                 __hip_atomic_store(READY + bh * 512 + ci, 1u, __ATOMIC_RELAXED, __HIP_MEMORY_SCOPE_AGENT);
.Lrfl0d:
	s_mov_b32 s90, -1
.Lprep_nopend:
	s_mov_b32 s90, s62

; #define LAS __attribute__((address_space(3)))
; #define MFMA32(a, b, c) __builtin_amdgcn_mfma_f32_16x16x32_bf16(a, b, c, 0, 0, 0)
; #define RD_PREFETCH_A(cc) do { const int soA_ = (b * SEQ + 16 * (cc)) * 256; \
;                 _Pragma("unroll") for (int ks = 0; ks < 3; ++ks) { nAW[ks] = __builtin_bit_cast(bf16x8, __builtin_amdgcn_raw_buffer_load_b128(rsWS, voA + 64 * ks, (int)WS_AW + soA_, 0)); nAA[ks] = __builtin_bit_cast(bf16x8, __builtin_amdgcn_raw_buffer_load_b128(rsWS, voA + 64 * ks, (int)WS_AA + soA_, 0)); } } while (0)
; __device__ void phase_rwkv_dist(const Params& p, LAS unsigned char* lds, int wg, int nwg) {
;     ...
;                 const size_t m = (size_t)b * SEQ + 16 * ci + r; const bool first = (16 * ci + r) == 0;
;                 f32x4 accw[4], acca[4];
; #pragma unroll
;                 for (int nt = 0; nt < 4; ++nt) { accw[nt] = zero4; acca[nt] = zero4; }
; #pragma unroll
;                 for (int ks = 0; ks < 3; ++ks)
; #pragma unroll
;                     for (int nt = 0; nt < 4; ++nt) { const int bo = (16 * nt * 104 + 32 * ks) * 2;
;                         accw[nt] = MFMA32(*(LAS const bf16x8*)(wb + bo), nAW[ks], accw[nt]); acca[nt] = MFMA32(*(LAS const bf16x8*)(wb + 13312 + bo), nAA[ks], acca[nt]); }
;                 __builtin_amdgcn_sched_barrier(0);
;                 if (cn < RC_NCHK) RD_PREFETCH_A(cn);
.LBB0_653:
	s_lshr_b32 s2, s43, 1
	s_mul_i32 s2, s2, 24
	s_bitcmp1_b32 s43, 0
	s_cselect_b32 s3, 3, 0
	s_add_i32 s2, s2, s16
	s_add_i32 s62, s2, s3
	s_add_i32 s43, s43, 1
	s_cmpk_gt_i32 s62, 0x1ff
	s_cbranch_scc1 .LBB0_652
	ds_read_b128 v[52:55], v138
	ds_read_b128 v[56:59], v138 offset:64
	ds_read_b128 v[60:63], v138 offset:13312
	ds_read_b128 v[64:67], v138 offset:13376
	ds_read_b128 v[68:71], v138 offset:3328
	ds_read_b128 v[72:75], v138 offset:128
	ds_read_b128 v[76:79], v138 offset:16640
	ds_read_b128 v[80:83], v138 offset:13440
	s_waitcnt vmcnt(20) lgkmcnt(7)
	v_mfma_f32_16x16x32_bf16 v[52:55], v[52:55], v[28:31], 0
	ds_read_b128 v[84:87], v138 offset:6656
	ds_read_b128 v[88:91], v138 offset:6720
	ds_read_b128 v[92:95], v138 offset:19968
	ds_read_b128 v[96:99], v138 offset:20032
	ds_read_b128 v[100:103], v138 offset:9984
	ds_read_b128 v[104:107], v138 offset:6784
	s_waitcnt vmcnt(19) lgkmcnt(11)
	v_mfma_f32_16x16x32_bf16 v[60:63], v[60:63], v[40:43], 0
	ds_read_b128 v[108:111], v138 offset:23296
	ds_read_b128 v[116:119], v138 offset:20096
	s_lshr_b32 s2, s43, 1
	s_mul_i32 s2, s2, 24
	s_waitcnt lgkmcnt(11)
	v_mfma_f32_16x16x32_bf16 v[68:71], v[68:71], v[28:31], 0
	s_bitcmp1_b32 s43, 0
	s_cselect_b32 s3, 3, 0
	s_add_i32 s2, s2, s16
	s_waitcnt vmcnt(18)
	v_mfma_f32_16x16x32_bf16 v[52:55], v[56:59], v[32:35], v[52:55]
	s_add_i32 s2, s2, s3
	s_lshl_b32 s3, s62, 11
	s_add_i32 s3, s3, s18
	s_waitcnt vmcnt(17)
	v_mfma_f32_16x16x32_bf16 v[56:59], v[64:67], v[44:47], v[60:63]
	s_nop 2
	ds_read_b128 v[60:63], v138 offset:3392
	ds_read_b128 v[64:67], v138 offset:3456
	s_add_i32 s6, s3, 0xffffff80
	s_cmp_gt_i32 s3, 0
	s_waitcnt lgkmcnt(11)
	v_mfma_f32_16x16x32_bf16 v[76:79], v[76:79], v[40:43], 0
	s_cselect_b32 s6, s6, 0
	s_cselect_b32 s7, 0, 0xffffff80
	s_add_i32 s38, s3, 0x13800000
	s_waitcnt lgkmcnt(9)
	v_mfma_f32_16x16x32_bf16 v[84:87], v[84:87], v[28:31], 0
	v_add_u32_e32 v0, s7, v191
	s_add_i32 s39, s6, 0x13800000
	s_add_i32 s3, s3, 0x17800000
	s_waitcnt lgkmcnt(1)
	v_mfma_f32_16x16x32_bf16 v[60:63], v[60:63], v[32:35], v[68:71]
	s_nop 2
	ds_read_b128 v[68:71], v138 offset:16704
	ds_read_b128 v[112:115], v138 offset:16768
	ds_read_b128 v[128:131], v138 offset:10112
	ds_read_b128 v[140:143], v138 offset:23424
	s_waitcnt lgkmcnt(3)
	v_mfma_f32_16x16x32_bf16 v[68:71], v[68:71], v[44:47], v[76:79]
	s_add_i32 s6, s6, 0x17800000
	s_nop 1
	ds_read_b128 v[76:79], v138 offset:10048
	v_mfma_f32_16x16x32_bf16 v[120:123], v[88:91], v[32:35], v[84:87]
	s_nop 2
	ds_read_b128 v[84:87], v138 offset:23360
	v_mfma_f32_16x16x32_bf16 v[92:95], v[92:95], v[40:43], 0
	v_mfma_f32_16x16x32_bf16 v[100:103], v[100:103], v[28:31], 0
	v_mfma_f32_16x16x32_bf16 v[108:111], v[108:111], v[40:43], 0
	v_mfma_f32_16x16x32_bf16 v[124:127], v[96:99], v[44:47], v[92:95]
	s_waitcnt vmcnt(16)
	v_mfma_f32_16x16x32_bf16 v[52:55], v[72:75], v[36:39], v[52:55]
	v_add_u32_e32 v73, s7, v208
	v_add_u32_e32 v72, s7, v207
	v_add_u32_e32 v74, s7, v209
	s_waitcnt lgkmcnt(1)
	v_mfma_f32_16x16x32_bf16 v[132:135], v[76:79], v[32:35], v[100:103]
	s_waitcnt lgkmcnt(0)
	v_mfma_f32_16x16x32_bf16 v[144:147], v[84:87], v[44:47], v[108:111]
	s_waitcnt vmcnt(15)
	v_mfma_f32_16x16x32_bf16 v[56:59], v[80:83], v[48:51], v[56:59]
	v_mfma_f32_16x16x32_bf16 v[84:87], v[64:67], v[36:39], v[60:63]
	v_mfma_f32_16x16x32_bf16 v[88:91], v[112:115], v[48:51], v[68:71]
	v_mfma_f32_16x16x32_bf16 v[76:79], v[104:107], v[36:39], v[120:123]
	v_mfma_f32_16x16x32_bf16 v[80:83], v[116:119], v[48:51], v[124:127]
	v_mfma_f32_16x16x32_bf16 v[68:71], v[128:131], v[36:39], v[132:135]
	v_mfma_f32_16x16x32_bf16 v[72:75], v[140:143], v[48:51], v[144:147]
	v_readfirstlane_b32 s81, v252
	s_cmp_ge_u32 s81, s32
	s_cselect_b64 s[92:93], -1, 0
	v_mov_b64_e32 v[60:61], v[220:221]
	v_mov_b64_e32 v[62:63], v[222:223]
	v_mov_b64_e32 v[112:113], v[224:225]
	v_mov_b64_e32 v[94:95], v[226:227]
	v_mov_b64_e32 v[64:65], v[228:229]
	v_mov_b64_e32 v[66:67], v[230:231]
	v_mov_b64_e32 v[114:115], v[232:233]
	v_mov_b64_e32 v[96:97], v[234:235]
	v_mov_b64_e32 v[118:119], v[236:237]
	v_mov_b64_e32 v[104:105], v[238:239]
	v_mov_b64_e32 v[100:101], v[240:241]
	v_mov_b64_e32 v[108:109], v[242:243]
	v_mov_b64_e32 v[120:121], v[244:245]
	v_mov_b64_e32 v[106:107], v[246:247]
	v_mov_b64_e32 v[102:103], v[248:249]
	v_mov_b64_e32 v[110:111], v[250:251]
	s_cmpk_gt_i32 s2, 0x1ff
	s_cbranch_scc1 .LBB0_656
	s_lshl_b32 s85, s2, 11
	s_add_i32 s85, s85, s18
	s_cmp_lt_i32 s2, 56
	s_cbranch_scc1 .Lprep_nopoll
	s_lshl_b32 s86, s2, 2
	s_add_u32 s86, s19, s86
	s_addc_u32 s87, s40, 0
	s_cmp_eq_u32 s91, 0
	s_cbranch_scc1 .Lpk0_a
	global_load_dword v252, v1, s[86:87] offset:-224 sc1
	s_branch .Lpk0_j
